# pool phase: loop-header store-drain wait removed, on top of the stacked version
# speedup vs baseline: 1.0127x; 1.0005x over previous
; DI float bf_lo(unsigned w) { return __uint_as_float(w << 16); }
; DI float bf_hi(unsigned w) { return __uint_as_float(w & 0xffff0000u); }
; DI int fresh_tid() { int t = threadIdx.x; asm volatile("" : "+v"(t)); return t; }
; DI int fresh_bid() { int t = blockIdx.x; asm volatile("" : "+s"(t)); return t; }
; template <int HW>
; DI void pool_item(const bf16_t* XN, const float* RSTD, bf16_t* P, int tok, int cg) {
;   const int tl = tok & (SEQ - 1);
;   u32x4 v[2 * HW]; float rsr[2 * HW];
; #pragma unroll
;   for (int i = 0; i < 2 * HW; ++i) {
;     int r = tl - HW + i; r = r < 0 ? 0 : (r > SEQ - 1 ? SEQ - 1 : r);
;     v[i] = *(const u32x4*)(XN + (size_t)(tok - tl + r) * DM + cg * 8); rsr[i] = 1.0f;
;   }
;   float s[8];
; #pragma unroll
;   for (int e = 0; e < 8; ++e) s[e] = 0.f;
; #pragma unroll
;   for (int i = 0; i < 2 * HW; ++i) {
;     const int r = tl - HW + i; const float m = (r >= 0 && r < SEQ) ? rsr[i] : 0.f;
;     s[0] += m * bf_lo(v[i].x); s[1] += m * bf_hi(v[i].x); s[2] += m * bf_lo(v[i].y); s[3] += m * bf_hi(v[i].y);
;     s[4] += m * bf_lo(v[i].z); s[5] += m * bf_hi(v[i].z); s[6] += m * bf_lo(v[i].w); s[7] += m * bf_hi(v[i].w);
; DI void pool_phase(const bf16_t* XN, const float* RSTD, bf16_t* P) {
;   const long nth = (long)gridDim.x * 512;
;   for (long it = (long)fresh_bid() * 512 + fresh_tid(); it < (long)MTOK * 256; it += nth) {
;     const int tok = (int)(it >> 8), cg = (int)(it & 255);
;     switch (cg >> 6) {
;       case 0: pool_item<1>(XN, RSTD, P, tok, cg); break;
;       case 1: pool_item<2>(XN, RSTD, P, tok, cg); break;
;       case 2: pool_item<4>(XN, RSTD, P, tok, cg); break;
;       default: pool_item<8>(XN, RSTD, P, tok, cg); break;
;     }
.LBB0_201:
	v_alignbit_b32 v15, v61, v60, 8
	v_lshrrev_b64 v[18:19], 8, v[60:61]
	v_and_b32_e32 v71, 0x3fff, v15
	v_cmp_lt_i32_e32 vcc, 1, v69
	s_and_saveexec_b64 s[12:13], vcc
	s_xor_b64 s[12:13], exec, s[12:13]
	s_cbranch_execz .LBB0_207
	v_add_u32_e32 v68, -4, v71
	v_add_u32_e32 v2, -3, v71
	v_cmp_lt_i32_e32 vcc, 2, v69
	v_min_u32_e32 v24, 0x3ffd, v71
	v_min_u32_e32 v33, 0x3ffc, v71
	v_max_i32_e32 v20, 0, v68
	v_max_i32_e32 v19, 0, v2
	s_and_saveexec_b64 s[18:19], vcc
	s_xor_b64 s[18:19], exec, s[18:19]
	s_cbranch_execz .LBB0_204
	v_add_u32_e32 v70, -8, v71
	v_and_b32_e32 v30, 0xffffc000, v15
	v_max_i32_e32 v4, 0, v70
	v_add_u32_e32 v72, -7, v71
	v_or_b32_e32 v4, v4, v30
	v_max_i32_e32 v6, 0, v72
	v_ashrrev_i32_e32 v5, 31, v4
	v_or_b32_e32 v6, v6, v30
	v_lshlrev_b64 v[4:5], 12, v[4:5]
	v_ashrrev_i32_e32 v7, 31, v6
	v_lshl_add_u64 v[4:5], v[62:63], 0, v[4:5]
	v_lshlrev_b64 v[6:7], 12, v[6:7]
	v_add_u32_e32 v73, -6, v71
	v_lshl_add_u64 v[6:7], v[62:63], 0, v[6:7]
	global_load_dwordx4 v[40:43], v[4:5], off
	global_load_dwordx4 v[36:39], v[6:7], off
	v_max_i32_e32 v4, 0, v73
	v_add_u32_e32 v74, -5, v71
	v_or_b32_e32 v4, v4, v30
	v_max_i32_e32 v6, 0, v74
	v_ashrrev_i32_e32 v5, 31, v4
	v_or_b32_e32 v6, v6, v30
	v_lshlrev_b64 v[4:5], 12, v[4:5]
	v_ashrrev_i32_e32 v7, 31, v6
	v_lshl_add_u64 v[4:5], v[62:63], 0, v[4:5]
	v_lshlrev_b64 v[6:7], 12, v[6:7]
	v_lshl_add_u64 v[6:7], v[62:63], 0, v[6:7]
	global_load_dwordx4 v[48:51], v[4:5], off
	global_load_dwordx4 v[44:47], v[6:7], off
	v_or_b32_e32 v4, v20, v30
	v_ashrrev_i32_e32 v5, 31, v4
	v_or_b32_e32 v6, v19, v30
	v_lshlrev_b64 v[4:5], 12, v[4:5]
	v_ashrrev_i32_e32 v7, 31, v6
	v_lshl_add_u64 v[4:5], v[62:63], 0, v[4:5]
	v_lshlrev_b64 v[6:7], 12, v[6:7]
	v_add_u32_e32 v75, -2, v71
	v_lshl_add_u64 v[6:7], v[62:63], 0, v[6:7]
	global_load_dwordx4 v[56:59], v[4:5], off
	global_load_dwordx4 v[52:55], v[6:7], off
	v_max_i32_e32 v4, 0, v75
	v_add_u32_e32 v76, -1, v71
	v_or_b32_e32 v4, v4, v30
	v_max_i32_e32 v6, 0, v76
	v_ashrrev_i32_e32 v5, 31, v4
	v_or_b32_e32 v6, v6, v30
	v_lshlrev_b64 v[4:5], 12, v[4:5]
	v_ashrrev_i32_e32 v7, 31, v6
	v_lshl_add_u64 v[4:5], v[62:63], 0, v[4:5]
	v_lshlrev_b64 v[6:7], 12, v[6:7]
	v_lshl_add_u64 v[6:7], v[62:63], 0, v[6:7]
	global_load_dwordx4 v[94:97], v[4:5], off
	global_load_dwordx4 v[98:101], v[6:7], off
	v_min_u32_e32 v6, 0x3ffe, v71
	v_or_b32_e32 v6, v6, v30
	v_add_u32_e32 v6, 1, v6
	v_mov_b32_e32 v4, v3
	v_mov_b32_e32 v5, v18
	v_ashrrev_i32_e32 v7, 31, v6
	v_or_b32_e32 v12, v24, v30
	v_or_b32_e32 v14, v33, v30
	v_ashrrev_i64 v[66:67], 20, v[4:5]
	v_lshlrev_b64 v[6:7], 12, v[6:7]
	v_add_u32_e32 v12, 2, v12
	v_add_u32_e32 v14, 3, v14
	v_min_u32_e32 v20, 0x3ffb, v71
	v_min_u32_e32 v22, 0x3ffa, v71
	v_lshl_add_u64 v[4:5], v[62:63], 0, v[66:67]
	v_lshl_add_u64 v[6:7], v[62:63], 0, v[6:7]
	v_ashrrev_i32_e32 v13, 31, v12
	v_ashrrev_i32_e32 v15, 31, v14
	v_or_b32_e32 v20, v20, v30
	v_or_b32_e32 v22, v22, v30
	global_load_dwordx4 v[8:11], v[4:5], off
	s_nop 0
	global_load_dwordx4 v[4:7], v[6:7], off
	v_lshlrev_b64 v[12:13], 12, v[12:13]
	v_lshlrev_b64 v[14:15], 12, v[14:15]
	v_add_u32_e32 v20, 4, v20
	v_add_u32_e32 v22, 5, v22
	v_min_u32_e32 v28, 0x3ff9, v71
	v_min_u32_e32 v77, 0x3ff8, v71
	v_lshl_add_u64 v[12:13], v[62:63], 0, v[12:13]
	v_lshl_add_u64 v[14:15], v[62:63], 0, v[14:15]
	v_ashrrev_i32_e32 v21, 31, v20
	v_ashrrev_i32_e32 v23, 31, v22
	v_or_b32_e32 v28, v28, v30
	v_or_b32_e32 v30, v77, v30
	global_load_dwordx4 v[16:19], v[12:13], off
	s_nop 0
	global_load_dwordx4 v[12:15], v[14:15], off
	v_lshlrev_b64 v[20:21], 12, v[20:21]
	v_lshlrev_b64 v[22:23], 12, v[22:23]
	v_add_u32_e32 v28, 6, v28
	v_add_u32_e32 v30, 7, v30
	v_lshl_add_u64 v[20:21], v[62:63], 0, v[20:21]
	v_lshl_add_u64 v[22:23], v[62:63], 0, v[22:23]
	v_ashrrev_i32_e32 v29, 31, v28
	v_ashrrev_i32_e32 v31, 31, v30
	global_load_dwordx4 v[24:27], v[20:21], off
	s_nop 0
	global_load_dwordx4 v[20:23], v[22:23], off
	v_lshlrev_b64 v[28:29], 12, v[28:29]
	v_lshlrev_b64 v[30:31], 12, v[30:31]
	v_lshl_add_u64 v[28:29], v[62:63], 0, v[28:29]
	v_lshl_add_u64 v[30:31], v[62:63], 0, v[30:31]
	global_load_dwordx4 v[32:35], v[28:29], off
	s_nop 0
	global_load_dwordx4 v[28:31], v[30:31], off
	s_movk_i32 s8, 0x4000
	v_cmp_gt_u32_e32 vcc, s8, v70
	s_waitcnt vmcnt(15)
	v_lshlrev_b32_e32 v112, 16, v42
	v_and_b32_e32 v113, 0xffff0000, v42
	v_cndmask_b32_e64 v102, 0, 1.0, vcc
	v_cmp_gt_u32_e32 vcc, s8, v72
	v_lshlrev_b32_e32 v90, 16, v43
	v_and_b32_e32 v91, 0xffff0000, v43
	v_cndmask_b32_e64 v104, 0, 1.0, vcc
	v_cmp_gt_u32_e32 vcc, s8, v73
	v_pk_fma_f32 v[112:113], v[102:103], v[112:113], 0 op_sel_hi:[0,1,0]
	s_waitcnt vmcnt(14)
	v_lshlrev_b32_e32 v114, 16, v38
	v_and_b32_e32 v115, 0xffff0000, v38
	v_cndmask_b32_e64 v106, 0, 1.0, vcc
	v_cmp_gt_u32_e32 vcc, s8, v74
	v_pk_fma_f32 v[90:91], v[102:103], v[90:91], 0 op_sel_hi:[0,1,0]
	v_lshlrev_b32_e32 v92, 16, v39
	v_and_b32_e32 v93, 0xffff0000, v39
	v_pk_fma_f32 v[38:39], v[104:105], v[114:115], v[112:113] op_sel_hi:[0,1,1]
	s_waitcnt vmcnt(13)
	v_lshlrev_b32_e32 v112, 16, v50
	v_and_b32_e32 v113, 0xffff0000, v50
	v_cndmask_b32_e64 v108, 0, 1.0, vcc
	v_cmp_gt_u32_e32 vcc, s8, v68
	v_pk_fma_f32 v[90:91], v[104:105], v[92:93], v[90:91] op_sel_hi:[0,1,1]
	v_lshlrev_b32_e32 v92, 16, v51
	v_and_b32_e32 v93, 0xffff0000, v51
	v_pk_fma_f32 v[38:39], v[106:107], v[112:113], v[38:39] op_sel_hi:[0,1,1]
	s_waitcnt vmcnt(12)
	v_lshlrev_b32_e32 v50, 16, v46
	v_and_b32_e32 v51, 0xffff0000, v46
	v_cndmask_b32_e64 v110, 0, 1.0, vcc
	v_pk_fma_f32 v[38:39], v[108:109], v[50:51], v[38:39] op_sel_hi:[0,1,1]
	s_waitcnt vmcnt(11)
; DI float bf_lo(unsigned w) { return __uint_as_float(w << 16); }
; DI float bf_hi(unsigned w) { return __uint_as_float(w & 0xffff0000u); }
; template <int HW>
; DI void pool_item(const bf16_t* XN, const float* RSTD, bf16_t* P, int tok, int cg) {
;     ...
; #pragma unroll
;   for (int i = 0; i < 2 * HW; ++i) {
;     const int r = tl - HW + i; const float m = (r >= 0 && r < SEQ) ? rsr[i] : 0.f;
;     s[0] += m * bf_lo(v[i].x); s[1] += m * bf_hi(v[i].x); s[2] += m * bf_lo(v[i].y); s[3] += m * bf_hi(v[i].y);
;     s[4] += m * bf_lo(v[i].z); s[5] += m * bf_hi(v[i].z); s[6] += m * bf_lo(v[i].w); s[7] += m * bf_hi(v[i].w);
;   }
	v_lshlrev_b32_e32 v50, 16, v58
	v_and_b32_e32 v51, 0xffff0000, v58
	v_pk_fma_f32 v[50:51], v[110:111], v[50:51], v[38:39] op_sel_hi:[0,1,1]
	v_lshlrev_b32_e32 v38, 16, v41
	v_and_b32_e32 v39, 0xffff0000, v41
	v_lshlrev_b32_e32 v114, 16, v40
	v_and_b32_e32 v115, 0xffff0000, v40
	v_pk_fma_f32 v[38:39], v[102:103], v[38:39], 0 op_sel_hi:[0,1,0]
	v_pk_fma_f32 v[40:41], v[102:103], v[114:115], 0 op_sel_hi:[0,1,0]
	v_lshlrev_b32_e32 v102, 16, v36
	v_and_b32_e32 v103, 0xffff0000, v36
	s_waitcnt vmcnt(8)
	v_and_b32_e32 v87, 0xffff0000, v101
	v_pk_fma_f32 v[90:91], v[106:107], v[92:93], v[90:91] op_sel_hi:[0,1,1]
	v_lshlrev_b32_e32 v92, 16, v47
	v_and_b32_e32 v93, 0xffff0000, v47
	v_lshlrev_b32_e32 v86, 16, v101
	v_and_b32_e32 v47, 0xffff0000, v100
	v_lshlrev_b32_e32 v46, 16, v100
	v_lshlrev_b32_e32 v100, 16, v37
	v_and_b32_e32 v101, 0xffff0000, v37
	v_pk_fma_f32 v[40:41], v[104:105], v[102:103], v[40:41] op_sel_hi:[0,1,1]
	v_lshlrev_b32_e32 v102, 16, v48
	v_and_b32_e32 v103, 0xffff0000, v48
	v_pk_fma_f32 v[38:39], v[104:105], v[100:101], v[38:39] op_sel_hi:[0,1,1]
	v_lshlrev_b32_e32 v100, 16, v49
	v_and_b32_e32 v101, 0xffff0000, v49
	v_pk_fma_f32 v[40:41], v[106:107], v[102:103], v[40:41] op_sel_hi:[0,1,1]
	v_lshlrev_b32_e32 v48, 16, v44
	v_and_b32_e32 v49, 0xffff0000, v44
	v_cmp_gt_u32_e32 vcc, s8, v2
	v_pk_fma_f32 v[38:39], v[106:107], v[100:101], v[38:39] op_sel_hi:[0,1,1]
	v_lshlrev_b32_e32 v100, 16, v45
	v_and_b32_e32 v101, 0xffff0000, v45
	v_pk_fma_f32 v[40:41], v[108:109], v[48:49], v[40:41] op_sel_hi:[0,1,1]
	v_lshlrev_b32_e32 v44, 16, v56
	v_and_b32_e32 v45, 0xffff0000, v56
	v_cndmask_b32_e64 v84, 0, 1.0, vcc
	v_cmp_gt_u32_e32 vcc, s8, v75
	v_pk_fma_f32 v[40:41], v[110:111], v[44:45], v[40:41] op_sel_hi:[0,1,1]
	v_lshlrev_b32_e32 v44, 16, v52
	v_and_b32_e32 v45, 0xffff0000, v52
	v_cndmask_b32_e64 v80, 0, 1.0, vcc
	v_cmp_gt_u32_e32 vcc, s8, v76
	v_pk_fma_f32 v[38:39], v[108:109], v[100:101], v[38:39] op_sel_hi:[0,1,1]
	v_lshlrev_b32_e32 v100, 16, v57
	v_and_b32_e32 v101, 0xffff0000, v57
	v_and_b32_e32 v37, 0xffff0000, v94
	v_lshlrev_b32_e32 v36, 16, v94
	v_pk_fma_f32 v[40:41], v[84:85], v[44:45], v[40:41] op_sel_hi:[0,1,1]
	v_cndmask_b32_e64 v82, 0, 1.0, vcc
	s_movk_i32 s8, 0x3fff
	v_pk_fma_f32 v[100:101], v[110:111], v[100:101], v[38:39] op_sel_hi:[0,1,1]
	v_and_b32_e32 v39, 0xffff0000, v98
	v_lshlrev_b32_e32 v38, 16, v98
	v_pk_fma_f32 v[36:37], v[80:81], v[36:37], v[40:41] op_sel_hi:[0,1,1]
	v_cmp_eq_u32_e32 vcc, s8, v71
	s_movk_i32 s8, 0x3ffe
	v_pk_fma_f32 v[38:39], v[82:83], v[38:39], v[36:37] op_sel_hi:[0,1,1]
	s_waitcnt vmcnt(7)
	v_lshlrev_b32_e32 v36, 16, v8
	v_and_b32_e32 v37, 0xffff0000, v8
	v_cndmask_b32_e64 v78, 1.0, 0, vcc
	v_cmp_gt_u32_e32 vcc, s8, v71
	s_movk_i32 s8, 0x3ffd
	v_pk_add_f32 v[38:39], v[38:39], v[36:37]
	s_waitcnt vmcnt(6)
	v_lshlrev_b32_e32 v40, 16, v4
	v_and_b32_e32 v41, 0xffff0000, v4
	v_cndmask_b32_e64 v76, 0, 1.0, vcc
	v_cmp_gt_u32_e32 vcc, s8, v71
	s_movk_i32 s8, 0x3ffc
	v_pk_fma_f32 v[38:39], v[78:79], v[40:41], v[38:39] op_sel_hi:[0,1,1]
	s_waitcnt vmcnt(5)
	v_lshlrev_b32_e32 v40, 16, v16
	v_and_b32_e32 v41, 0xffff0000, v16
	v_cndmask_b32_e64 v74, 0, 1.0, vcc
	v_cmp_gt_u32_e32 vcc, s8, v71
	s_movk_i32 s8, 0x3ffb
	v_pk_fma_f32 v[38:39], v[76:77], v[40:41], v[38:39] op_sel_hi:[0,1,1]
	s_waitcnt vmcnt(4)
	v_lshlrev_b32_e32 v40, 16, v12
	v_and_b32_e32 v41, 0xffff0000, v12
	v_cndmask_b32_e64 v72, 0, 1.0, vcc
	v_cmp_gt_u32_e32 vcc, s8, v71
	s_movk_i32 s8, 0x3ffa
	v_pk_fma_f32 v[38:39], v[74:75], v[40:41], v[38:39] op_sel_hi:[0,1,1]
	s_waitcnt vmcnt(3)
	v_lshlrev_b32_e32 v40, 16, v24
	v_and_b32_e32 v41, 0xffff0000, v24
	v_cndmask_b32_e64 v70, 0, 1.0, vcc
	v_cmp_gt_u32_e32 vcc, s8, v71
	s_movk_i32 s8, 0x3ff9
	v_pk_fma_f32 v[38:39], v[72:73], v[40:41], v[38:39] op_sel_hi:[0,1,1]
	s_waitcnt vmcnt(2)
	v_lshlrev_b32_e32 v40, 16, v20
	v_and_b32_e32 v41, 0xffff0000, v20
	v_cndmask_b32_e64 v68, 0, 1.0, vcc
	v_cmp_gt_u32_e32 vcc, s8, v71
	v_pk_fma_f32 v[38:39], v[70:71], v[40:41], v[38:39] op_sel_hi:[0,1,1]
	s_waitcnt vmcnt(1)
	v_lshlrev_b32_e32 v40, 16, v32
	v_and_b32_e32 v41, 0xffff0000, v32
	v_cndmask_b32_e64 v2, 0, 1.0, vcc
	v_pk_fma_f32 v[90:91], v[108:109], v[92:93], v[90:91] op_sel_hi:[0,1,1]
	v_lshlrev_b32_e32 v92, 16, v59
	v_and_b32_e32 v93, 0xffff0000, v59
	v_lshlrev_b32_e32 v112, 16, v53
	v_and_b32_e32 v113, 0xffff0000, v53
	v_pk_fma_f32 v[38:39], v[68:69], v[40:41], v[38:39] op_sel_hi:[0,1,1]
	s_waitcnt vmcnt(0)
; DI unsigned cvt_pk_bf16(float lo, float hi) { const f32x2 v = {lo, hi}; const bf16x2_t r = __builtin_convertvector(v, bf16x2_t); return __builtin_bit_cast(unsigned, r); }
; DI float bf_lo(unsigned w) { return __uint_as_float(w << 16); }
; DI float bf_hi(unsigned w) { return __uint_as_float(w & 0xffff0000u); }
; template <int HW>
; DI void pool_item(const bf16_t* XN, const float* RSTD, bf16_t* P, int tok, int cg) {
;     ...
; #pragma unroll
;   for (int i = 0; i < 2 * HW; ++i) {
;     const int r = tl - HW + i; const float m = (r >= 0 && r < SEQ) ? rsr[i] : 0.f;
;     s[0] += m * bf_lo(v[i].x); s[1] += m * bf_hi(v[i].x); s[2] += m * bf_lo(v[i].y); s[3] += m * bf_hi(v[i].y);
;     s[4] += m * bf_lo(v[i].z); s[5] += m * bf_hi(v[i].z); s[6] += m * bf_lo(v[i].w); s[7] += m * bf_hi(v[i].w);
;   }
;   const int lo = tl - HW < 0 ? 0 : tl - HW, hi = tl + HW > SEQ ? SEQ : tl + HW;
;   const float inv = 1.0f / (float)(hi - lo);
;   const u32x4 c = v[HW]; const float rc = rsr[HW];
;   u32x4 w;
;   w.x = cvt_pk_bf16(s[0] * inv - rc * bf_lo(c.x), s[1] * inv - rc * bf_hi(c.x)); w.y = cvt_pk_bf16(s[2] * inv - rc * bf_lo(c.y), s[3] * inv - rc * bf_hi(c.y));
;   w.z = cvt_pk_bf16(s[4] * inv - rc * bf_lo(c.z), s[5] * inv - rc * bf_hi(c.z)); w.w = cvt_pk_bf16(s[6] * inv - rc * bf_lo(c.w), s[7] * inv - rc * bf_hi(c.w));
;   *(u32x4*)(P + (size_t)tok * DM + cg * 8) = w;
	v_lshlrev_b32_e32 v40, 16, v28
	v_and_b32_e32 v41, 0xffff0000, v28
	v_pk_fma_f32 v[90:91], v[110:111], v[92:93], v[90:91] op_sel_hi:[0,1,1]
	v_lshlrev_b32_e32 v92, 16, v55
	v_and_b32_e32 v93, 0xffff0000, v55
	v_lshlrev_b32_e32 v58, 16, v54
	v_and_b32_e32 v59, 0xffff0000, v54
	v_and_b32_e32 v55, 0xffff0000, v95
	v_lshlrev_b32_e32 v54, 16, v95
	v_pk_fma_f32 v[38:39], v[2:3], v[40:41], v[38:39] op_sel_hi:[0,1,1]
	v_pk_fma_f32 v[40:41], v[84:85], v[112:113], v[100:101] op_sel_hi:[0,1,1]
	v_and_b32_e32 v89, 0xffff0000, v97
	v_lshlrev_b32_e32 v88, 16, v97
	v_and_b32_e32 v43, 0xffff0000, v96
	v_lshlrev_b32_e32 v42, 16, v96
	v_and_b32_e32 v97, 0xffff0000, v99
	v_lshlrev_b32_e32 v96, 16, v99
	v_pk_fma_f32 v[40:41], v[80:81], v[54:55], v[40:41] op_sel_hi:[0,1,1]
	v_pk_fma_f32 v[40:41], v[82:83], v[96:97], v[40:41] op_sel_hi:[0,1,1]
	v_lshlrev_b32_e32 v8, 16, v9
	v_and_b32_e32 v9, 0xffff0000, v9
	v_pk_add_f32 v[40:41], v[40:41], v[8:9]
	v_lshlrev_b32_e32 v4, 16, v5
	v_and_b32_e32 v5, 0xffff0000, v5
	v_pk_fma_f32 v[4:5], v[78:79], v[4:5], v[40:41] op_sel_hi:[0,1,1]
	v_lshlrev_b32_e32 v16, 16, v17
	v_and_b32_e32 v17, 0xffff0000, v17
	v_pk_fma_f32 v[4:5], v[76:77], v[16:17], v[4:5] op_sel_hi:[0,1,1]
	v_lshlrev_b32_e32 v12, 16, v13
	v_and_b32_e32 v13, 0xffff0000, v13
	v_pk_fma_f32 v[4:5], v[74:75], v[12:13], v[4:5] op_sel_hi:[0,1,1]
	v_lshlrev_b32_e32 v12, 16, v25
	v_and_b32_e32 v13, 0xffff0000, v25
	v_pk_fma_f32 v[4:5], v[72:73], v[12:13], v[4:5] op_sel_hi:[0,1,1]
	v_lshlrev_b32_e32 v12, 16, v21
	v_and_b32_e32 v13, 0xffff0000, v21
	v_pk_fma_f32 v[4:5], v[70:71], v[12:13], v[4:5] op_sel_hi:[0,1,1]
	v_lshlrev_b32_e32 v12, 16, v33
	v_and_b32_e32 v13, 0xffff0000, v33
	v_pk_fma_f32 v[4:5], v[68:69], v[12:13], v[4:5] op_sel_hi:[0,1,1]
	v_lshlrev_b32_e32 v12, 16, v29
	v_and_b32_e32 v13, 0xffff0000, v29
	v_pk_fma_f32 v[4:5], v[2:3], v[12:13], v[4:5] op_sel_hi:[0,1,1]
	v_pk_fma_f32 v[12:13], v[84:85], v[58:59], v[50:51] op_sel_hi:[0,1,1]
	v_pk_fma_f32 v[12:13], v[80:81], v[42:43], v[12:13] op_sel_hi:[0,1,1]
	v_pk_fma_f32 v[16:17], v[82:83], v[46:47], v[12:13] op_sel_hi:[0,1,1]
	v_lshlrev_b32_e32 v12, 16, v10
	v_and_b32_e32 v13, 0xffff0000, v10
	v_pk_add_f32 v[16:17], v[16:17], v[12:13]
	v_lshlrev_b32_e32 v20, 16, v6
	v_and_b32_e32 v21, 0xffff0000, v6
	v_pk_fma_f32 v[16:17], v[78:79], v[20:21], v[16:17] op_sel_hi:[0,1,1]
	v_lshlrev_b32_e32 v20, 16, v18
	v_and_b32_e32 v21, 0xffff0000, v18
	v_pk_fma_f32 v[16:17], v[76:77], v[20:21], v[16:17] op_sel_hi:[0,1,1]
	v_lshlrev_b32_e32 v20, 16, v14
	v_and_b32_e32 v21, 0xffff0000, v14
	v_pk_fma_f32 v[16:17], v[74:75], v[20:21], v[16:17] op_sel_hi:[0,1,1]
	v_lshlrev_b32_e32 v20, 16, v26
	v_and_b32_e32 v21, 0xffff0000, v26
	v_pk_fma_f32 v[16:17], v[72:73], v[20:21], v[16:17] op_sel_hi:[0,1,1]
	v_lshlrev_b32_e32 v20, 16, v22
	v_and_b32_e32 v21, 0xffff0000, v22
	v_pk_fma_f32 v[16:17], v[70:71], v[20:21], v[16:17] op_sel_hi:[0,1,1]
	v_lshlrev_b32_e32 v20, 16, v34
	v_and_b32_e32 v21, 0xffff0000, v34
	v_pk_fma_f32 v[16:17], v[68:69], v[20:21], v[16:17] op_sel_hi:[0,1,1]
	v_lshlrev_b32_e32 v20, 16, v30
	v_and_b32_e32 v21, 0xffff0000, v30
	v_pk_fma_f32 v[16:17], v[2:3], v[20:21], v[16:17] op_sel_hi:[0,1,1]
	v_pk_fma_f32 v[20:21], v[84:85], v[92:93], v[90:91] op_sel_hi:[0,1,1]
	v_pk_fma_f32 v[20:21], v[80:81], v[88:89], v[20:21] op_sel_hi:[0,1,1]
	v_pk_fma_f32 v[20:21], v[82:83], v[86:87], v[20:21] op_sel_hi:[0,1,1]
	v_lshlrev_b32_e32 v10, 16, v11
	v_and_b32_e32 v11, 0xffff0000, v11
	v_pk_add_f32 v[20:21], v[20:21], v[10:11]
	v_lshlrev_b32_e32 v6, 16, v7
	v_and_b32_e32 v7, 0xffff0000, v7
	v_pk_fma_f32 v[6:7], v[78:79], v[6:7], v[20:21] op_sel_hi:[0,1,1]
	v_lshlrev_b32_e32 v18, 16, v19
	v_and_b32_e32 v19, 0xffff0000, v19
	v_pk_fma_f32 v[6:7], v[76:77], v[18:19], v[6:7] op_sel_hi:[0,1,1]
	v_lshlrev_b32_e32 v14, 16, v15
	v_and_b32_e32 v15, 0xffff0000, v15
	v_pk_fma_f32 v[6:7], v[74:75], v[14:15], v[6:7] op_sel_hi:[0,1,1]
	v_lshlrev_b32_e32 v14, 16, v27
	v_and_b32_e32 v15, 0xffff0000, v27
	v_pk_fma_f32 v[6:7], v[72:73], v[14:15], v[6:7] op_sel_hi:[0,1,1]
	v_lshlrev_b32_e32 v14, 16, v23
	v_and_b32_e32 v15, 0xffff0000, v23
	v_pk_fma_f32 v[6:7], v[70:71], v[14:15], v[6:7] op_sel_hi:[0,1,1]
	v_lshlrev_b32_e32 v14, 16, v35
	v_and_b32_e32 v15, 0xffff0000, v35
	v_pk_fma_f32 v[6:7], v[68:69], v[14:15], v[6:7] op_sel_hi:[0,1,1]
	v_lshlrev_b32_e32 v14, 16, v31
	v_and_b32_e32 v15, 0xffff0000, v31
	v_pk_fma_f32 v[6:7], v[2:3], v[14:15], v[6:7] op_sel_hi:[0,1,1]
	v_max_u32_e32 v2, 8, v71
	v_sub_u32_e32 v2, v77, v2
	v_add_u32_e32 v14, 16, v2
